# v35 + FFN-in GEMM epilogue: the per-row-group LN stat (mu,rstd) LDS reads are all issued at the epilogue start into free registers instead of one exposed ds_read+wait per row group
# speedup vs baseline: 1.0035x; 1.0035x over previous
.LBB0_1099:
	s_add_u32 s62, s36, 0x100
	s_addc_u32 s63, s37, 0
	s_add_i32 s84, 0, 0x10000
	v_add_u32_e32 v70, s84, v170
	ds_read_b128 v[58:61], v70
	ds_read_b128 v[62:65], v70 offset:1024
	ds_read_b128 v[66:69], v70 offset:2048
	ds_read_b128 v[70:73], v70 offset:3072
	s_cmp_eq_u32 s83, 12
	s_cselect_b32 s67, s59, s63
	s_cselect_b32 s66, s78, s62
	s_cselect_b32 s65, s79, s82
	s_cselect_b32 s64, s80, s81
	v_lshl_add_u64 v[192:193], s[36:37], 0, v[168:169]
	s_add_i32 m0, s69, 0xc000
	ds_read_b128 v[78:81], v175
	ds_read_b128 v[86:89], v175 offset:1024
	ds_read_b128 v[90:93], v175 offset:2048
	ds_read_b128 v[94:97], v175 offset:3072
	ds_read_b128 v[176:179], v175 offset:4096
	ds_read_b128 v[180:183], v175 offset:5120
	ds_read_b128 v[184:187], v175 offset:6144
	ds_read_b128 v[188:191], v175 offset:7168
	global_load_lds_dwordx4 v[192:193], off
	v_lshl_add_u64 v[192:193], s[36:37], 0, v[166:167]
	s_add_i32 m0, s69, 0xe000
	s_nop 0
	global_load_lds_dwordx4 v[192:193], off
	s_waitcnt lgkmcnt(8)
	s_barrier
	s_waitcnt lgkmcnt(0)
	s_waitcnt lgkmcnt(0)
	v_mfma_f32_16x16x32_bf16 v[158:161], v[58:61], v[78:81], v[158:161]
	v_mfma_f32_16x16x32_bf16 v[150:153], v[66:69], v[78:81], v[150:153]
	v_mfma_f32_16x16x32_bf16 v[142:145], v[58:61], v[90:93], v[142:145]
	v_mfma_f32_16x16x32_bf16 v[134:137], v[66:69], v[90:93], v[134:137]
	v_mfma_f32_16x16x32_bf16 v[126:129], v[58:61], v[176:179], v[126:129]
	v_mfma_f32_16x16x32_bf16 v[118:121], v[66:69], v[176:179], v[118:121]
	v_mfma_f32_16x16x32_bf16 v[110:113], v[58:61], v[184:187], v[110:113]
	v_mfma_f32_16x16x32_bf16 v[102:105], v[66:69], v[184:187], v[102:105]
	v_mfma_f32_16x16x32_bf16 v[158:161], v[62:65], v[86:89], v[158:161]
	v_mfma_f32_16x16x32_bf16 v[150:153], v[70:73], v[86:89], v[150:153]
	v_mfma_f32_16x16x32_bf16 v[142:145], v[62:65], v[94:97], v[142:145]
	v_mfma_f32_16x16x32_bf16 v[134:137], v[70:73], v[94:97], v[134:137]
	v_mfma_f32_16x16x32_bf16 v[126:129], v[62:65], v[180:183], v[126:129]
	v_mfma_f32_16x16x32_bf16 v[118:121], v[70:73], v[180:183], v[118:121]
	v_mfma_f32_16x16x32_bf16 v[110:113], v[62:65], v[188:191], v[110:113]
	v_mfma_f32_16x16x32_bf16 v[102:105], v[70:73], v[188:191], v[102:105]
	s_barrier
	s_add_i32 s85, 0, 0x14000
	v_add_u32_e32 v192, s85, v170
	s_add_i32 s36, s84, s68
	ds_read_b128 v[200:203], v192
	ds_read_b128 v[204:207], v192 offset:1024
	ds_read_b128 v[208:211], v192 offset:2048
	ds_read_b128 v[222:225], v192 offset:3072
	v_lshl_add_u64 v[192:193], s[64:65], 0, v[164:165]
	s_mov_b32 m0, s36
	v_lshl_add_u64 v[214:215], s[64:65], 0, v[162:163]
	global_load_lds_dwordx4 v[192:193], off
	s_add_i32 m0, s36, 0x2000
	s_nop 0
	global_load_lds_dwordx4 v[214:215], off
	s_barrier
	s_waitcnt lgkmcnt(0)
	s_waitcnt lgkmcnt(0)
	v_mfma_f32_16x16x32_bf16 v[154:157], v[200:203], v[78:81], v[154:157]
	v_mfma_f32_16x16x32_bf16 v[78:81], v[208:211], v[78:81], v[146:149]
	v_mfma_f32_16x16x32_bf16 v[154:157], v[204:207], v[86:89], v[154:157]
	v_mfma_f32_16x16x32_bf16 v[78:81], v[222:225], v[86:89], v[78:81]
	v_mfma_f32_16x16x32_bf16 v[86:89], v[200:203], v[90:93], v[138:141]
	v_mfma_f32_16x16x32_bf16 v[90:93], v[208:211], v[90:93], v[130:133]
	v_mfma_f32_16x16x32_bf16 v[114:117], v[208:211], v[176:179], v[114:117]
	v_mfma_f32_16x16x32_bf16 v[106:109], v[200:203], v[184:187], v[106:109]
	v_mfma_f32_16x16x32_bf16 v[98:101], v[208:211], v[184:187], v[98:101]
	v_mfma_f32_16x16x32_bf16 v[86:89], v[204:207], v[94:97], v[86:89]
	v_mfma_f32_16x16x32_bf16 v[90:93], v[222:225], v[94:97], v[90:93]
	v_mfma_f32_16x16x32_bf16 v[94:97], v[200:203], v[176:179], v[122:125]
	v_mfma_f32_16x16x32_bf16 v[114:117], v[222:225], v[180:183], v[114:117]
	v_mfma_f32_16x16x32_bf16 v[106:109], v[204:207], v[188:191], v[106:109]
	v_mfma_f32_16x16x32_bf16 v[98:101], v[222:225], v[188:191], v[98:101]
	v_mfma_f32_16x16x32_bf16 v[94:97], v[204:207], v[180:183], v[94:97]
	s_mov_b32 m0, s69
	v_lshl_add_u64 v[234:235], s[66:67], 0, v[164:165]
	s_barrier
	ds_read_b128 v[122:125], v175 offset:16384
	ds_read_b128 v[130:133], v175 offset:17408
	ds_read_b128 v[138:141], v175 offset:18432
	ds_read_b128 v[146:149], v175 offset:19456
	ds_read_b128 v[176:179], v175 offset:20480
	ds_read_b128 v[180:183], v175 offset:21504
	ds_read_b128 v[184:187], v175 offset:22528
	ds_read_b128 v[188:191], v175 offset:23552
	global_load_lds_dwordx4 v[234:235], off
	v_lshl_add_u64 v[236:237], s[66:67], 0, v[162:163]
	s_mov_b32 m0, s70
	s_nop 0
	global_load_lds_dwordx4 v[236:237], off
	s_barrier
	s_waitcnt lgkmcnt(0)
	s_waitcnt lgkmcnt(0)
	v_mfma_f32_16x16x32_bf16 v[82:85], v[58:61], v[122:125], v[82:85]
	v_mfma_f32_16x16x32_bf16 v[54:57], v[66:69], v[122:125], v[54:57]
	v_mfma_f32_16x16x32_bf16 v[46:49], v[58:61], v[138:141], v[46:49]
	v_mfma_f32_16x16x32_bf16 v[38:41], v[66:69], v[138:141], v[38:41]
	v_mfma_f32_16x16x32_bf16 v[30:33], v[58:61], v[176:179], v[30:33]
	v_mfma_f32_16x16x32_bf16 v[22:25], v[66:69], v[176:179], v[22:25]
	v_mfma_f32_16x16x32_bf16 v[14:17], v[58:61], v[184:187], v[14:17]
	v_mfma_f32_16x16x32_bf16 v[6:9], v[66:69], v[184:187], v[6:9]
	v_mfma_f32_16x16x32_bf16 v[82:85], v[62:65], v[130:133], v[82:85]
	v_mfma_f32_16x16x32_bf16 v[54:57], v[70:73], v[130:133], v[54:57]
	v_mfma_f32_16x16x32_bf16 v[46:49], v[62:65], v[146:149], v[46:49]
	v_mfma_f32_16x16x32_bf16 v[38:41], v[70:73], v[146:149], v[38:41]
	v_mfma_f32_16x16x32_bf16 v[30:33], v[62:65], v[180:183], v[30:33]
	v_mfma_f32_16x16x32_bf16 v[22:25], v[70:73], v[180:183], v[22:25]
	v_mfma_f32_16x16x32_bf16 v[14:17], v[62:65], v[188:191], v[14:17]
	v_mfma_f32_16x16x32_bf16 v[6:9], v[70:73], v[188:191], v[6:9]
	s_barrier
	s_add_u32 s36, s64, 0x40000
	s_addc_u32 s37, s65, 0
	s_add_i32 s84, s85, s68
	v_lshl_add_u64 v[58:59], s[36:37], 0, v[164:165]
	s_mov_b32 m0, s84
	s_nop 0
	global_load_lds_dwordx4 v[58:59], off
	v_lshl_add_u64 v[58:59], s[36:37], 0, v[162:163]
	s_add_i32 m0, s84, 0x2000
	s_nop 0
	global_load_lds_dwordx4 v[58:59], off
	s_waitcnt vmcnt(6)
	s_barrier
	v_mfma_f32_16x16x32_bf16 v[50:53], v[208:211], v[122:125], v[50:53]
	v_mfma_f32_16x16x32_bf16 v[42:45], v[200:203], v[138:141], v[42:45]
	v_mfma_f32_16x16x32_bf16 v[34:37], v[208:211], v[138:141], v[34:37]
	v_mfma_f32_16x16x32_bf16 v[26:29], v[200:203], v[176:179], v[26:29]
	v_mfma_f32_16x16x32_bf16 v[18:21], v[208:211], v[176:179], v[18:21]
	v_mfma_f32_16x16x32_bf16 v[10:13], v[200:203], v[184:187], v[10:13]
	v_mfma_f32_16x16x32_bf16 v[2:5], v[208:211], v[184:187], v[2:5]
	v_mfma_f32_16x16x32_bf16 v[58:61], v[200:203], v[122:125], v[74:77]
	v_mfma_f32_16x16x32_bf16 v[50:53], v[222:225], v[130:133], v[50:53]
	v_mfma_f32_16x16x32_bf16 v[42:45], v[204:207], v[146:149], v[42:45]
	v_mfma_f32_16x16x32_bf16 v[34:37], v[222:225], v[146:149], v[34:37]
	v_mfma_f32_16x16x32_bf16 v[26:29], v[204:207], v[180:183], v[26:29]
	v_mfma_f32_16x16x32_bf16 v[18:21], v[222:225], v[180:183], v[18:21]
	v_mfma_f32_16x16x32_bf16 v[10:13], v[204:207], v[188:191], v[10:13]
	v_mfma_f32_16x16x32_bf16 v[2:5], v[222:225], v[188:191], v[2:5]
	v_mfma_f32_16x16x32_bf16 v[58:61], v[204:207], v[130:133], v[58:61]
	s_add_i32 s84, 0, 0x18000
	v_add_u32_e32 v74, s84, v170
	s_barrier
	ds_read_b128 v[62:65], v74
	ds_read_b128 v[66:69], v74 offset:1024
	ds_read_b128 v[70:73], v74 offset:2048
	ds_read_b128 v[74:77], v74 offset:3072
	s_add_u32 s36, s66, 0x40000
	s_addc_u32 s37, s67, 0
	s_mov_b32 m0, s71
	v_lshl_add_u64 v[138:139], s[36:37], 0, v[164:165]
	ds_read_b128 v[122:125], v175 offset:32768
	ds_read_b128 v[130:133], v175 offset:33792
	ds_read_b128 v[176:179], v175 offset:34816
	ds_read_b128 v[180:183], v175 offset:35840
	ds_read_b128 v[184:187], v175 offset:36864
	ds_read_b128 v[188:191], v175 offset:37888
	ds_read_b128 v[200:203], v175 offset:38912
	ds_read_b128 v[204:207], v175 offset:39936
	global_load_lds_dwordx4 v[138:139], off
	v_lshl_add_u64 v[138:139], s[36:37], 0, v[162:163]
	s_mov_b32 m0, s72
	s_nop 0
	global_load_lds_dwordx4 v[138:139], off
	s_waitcnt lgkmcnt(8)
	s_barrier
	s_waitcnt lgkmcnt(0)
	s_waitcnt lgkmcnt(0)
	v_mfma_f32_16x16x32_bf16 v[138:141], v[62:65], v[122:125], v[158:161]
	v_mfma_f32_16x16x32_bf16 v[158:161], v[66:69], v[130:133], v[138:141]
	v_mfma_f32_16x16x32_bf16 v[138:141], v[70:73], v[122:125], v[150:153]
	v_mfma_f32_16x16x32_bf16 v[150:153], v[74:77], v[130:133], v[138:141]
	v_mfma_f32_16x16x32_bf16 v[138:141], v[62:65], v[176:179], v[142:145]
	v_mfma_f32_16x16x32_bf16 v[134:137], v[70:73], v[176:179], v[134:137]
	v_mfma_f32_16x16x32_bf16 v[126:129], v[62:65], v[184:187], v[126:129]
	v_mfma_f32_16x16x32_bf16 v[118:121], v[70:73], v[184:187], v[118:121]
	v_mfma_f32_16x16x32_bf16 v[110:113], v[62:65], v[200:203], v[110:113]
	v_mfma_f32_16x16x32_bf16 v[102:105], v[70:73], v[200:203], v[102:105]
	v_mfma_f32_16x16x32_bf16 v[142:145], v[66:69], v[180:183], v[138:141]
	v_mfma_f32_16x16x32_bf16 v[134:137], v[74:77], v[180:183], v[134:137]
	v_mfma_f32_16x16x32_bf16 v[126:129], v[66:69], v[188:191], v[126:129]
	v_mfma_f32_16x16x32_bf16 v[118:121], v[74:77], v[188:191], v[118:121]
	v_mfma_f32_16x16x32_bf16 v[110:113], v[66:69], v[204:207], v[110:113]
	v_mfma_f32_16x16x32_bf16 v[102:105], v[74:77], v[204:207], v[102:105]
	s_barrier
	s_add_i32 s66, 0, 0x1c000
	v_add_u32_e32 v138, s66, v170
	s_add_i32 s36, s84, s68
	ds_read_b128 v[208:211], v138
	ds_read_b128 v[222:225], v138 offset:1024
	ds_read_b128 v[226:229], v138 offset:2048
	ds_read_b128 v[230:233], v138 offset:3072
	v_lshl_add_u64 v[138:139], v[192:193], 0, s[22:23]
	s_mov_b32 m0, s36
	s_nop 0
	global_load_lds_dwordx4 v[138:139], off
	v_lshl_add_u64 v[138:139], v[214:215], 0, s[22:23]
	s_add_i32 m0, s36, 0x2000
	s_nop 0
	global_load_lds_dwordx4 v[138:139], off
	s_barrier
	s_waitcnt lgkmcnt(0)
	s_waitcnt lgkmcnt(0)
	v_mfma_f32_16x16x32_bf16 v[78:81], v[226:229], v[122:125], v[78:81]
	v_mfma_f32_16x16x32_bf16 v[138:141], v[208:211], v[122:125], v[154:157]
	v_mfma_f32_16x16x32_bf16 v[146:149], v[230:233], v[130:133], v[78:81]
	v_mfma_f32_16x16x32_bf16 v[78:81], v[208:211], v[176:179], v[86:89]
	v_mfma_f32_16x16x32_bf16 v[154:157], v[222:225], v[130:133], v[138:141]
	v_mfma_f32_16x16x32_bf16 v[138:141], v[222:225], v[180:183], v[78:81]
	v_mfma_f32_16x16x32_bf16 v[78:81], v[226:229], v[176:179], v[90:93]
	v_mfma_f32_16x16x32_bf16 v[130:133], v[230:233], v[180:183], v[78:81]
	v_mfma_f32_16x16x32_bf16 v[78:81], v[208:211], v[184:187], v[94:97]
	v_mfma_f32_16x16x32_bf16 v[122:125], v[222:225], v[188:191], v[78:81]
	v_mfma_f32_16x16x32_bf16 v[78:81], v[226:229], v[184:187], v[114:117]
	v_mfma_f32_16x16x32_bf16 v[114:117], v[230:233], v[188:191], v[78:81]
	v_mfma_f32_16x16x32_bf16 v[78:81], v[208:211], v[200:203], v[106:109]
	v_mfma_f32_16x16x32_bf16 v[106:109], v[222:225], v[204:207], v[78:81]
	v_mfma_f32_16x16x32_bf16 v[78:81], v[226:229], v[200:203], v[98:101]
	v_mfma_f32_16x16x32_bf16 v[98:101], v[230:233], v[204:207], v[78:81]
	s_mov_b32 m0, s73
	v_lshl_add_u64 v[192:193], v[234:235], 0, s[22:23]
	s_barrier
	s_nop 2
	ds_read_b128 v[78:81], v175 offset:49152
	ds_read_b128 v[86:89], v175 offset:50176
	ds_read_b128 v[90:93], v175 offset:51200
	ds_read_b128 v[94:97], v175 offset:52224
	ds_read_b128 v[176:179], v175 offset:53248
	ds_read_b128 v[180:183], v175 offset:54272
	ds_read_b128 v[184:187], v175 offset:55296
	ds_read_b128 v[188:191], v175 offset:56320
	global_load_lds_dwordx4 v[192:193], off
	v_lshl_add_u64 v[192:193], v[236:237], 0, s[22:23]
	s_mov_b32 m0, s75
	s_nop 0
	global_load_lds_dwordx4 v[192:193], off
	s_barrier
	s_waitcnt lgkmcnt(0)
	s_waitcnt lgkmcnt(0)
	v_mfma_f32_16x16x32_bf16 v[82:85], v[62:65], v[78:81], v[82:85]
	v_mfma_f32_16x16x32_bf16 v[54:57], v[70:73], v[78:81], v[54:57]
	v_mfma_f32_16x16x32_bf16 v[46:49], v[62:65], v[90:93], v[46:49]
	v_mfma_f32_16x16x32_bf16 v[38:41], v[70:73], v[90:93], v[38:41]
	v_mfma_f32_16x16x32_bf16 v[30:33], v[62:65], v[176:179], v[30:33]
	v_mfma_f32_16x16x32_bf16 v[22:25], v[70:73], v[176:179], v[22:25]
	v_mfma_f32_16x16x32_bf16 v[14:17], v[62:65], v[184:187], v[14:17]
	v_mfma_f32_16x16x32_bf16 v[6:9], v[70:73], v[184:187], v[6:9]
	v_mfma_f32_16x16x32_bf16 v[82:85], v[66:69], v[86:89], v[82:85]
	v_mfma_f32_16x16x32_bf16 v[54:57], v[74:77], v[86:89], v[54:57]
	v_mfma_f32_16x16x32_bf16 v[46:49], v[66:69], v[94:97], v[46:49]
	v_mfma_f32_16x16x32_bf16 v[38:41], v[74:77], v[94:97], v[38:41]
	v_mfma_f32_16x16x32_bf16 v[30:33], v[66:69], v[180:183], v[30:33]
	v_mfma_f32_16x16x32_bf16 v[22:25], v[74:77], v[180:183], v[22:25]
	v_mfma_f32_16x16x32_bf16 v[14:17], v[66:69], v[188:191], v[14:17]
	v_mfma_f32_16x16x32_bf16 v[6:9], v[74:77], v[188:191], v[6:9]
	s_barrier
	s_add_u32 s36, s64, 0x40080
	s_addc_u32 s37, s65, 0
	s_add_i32 s64, s66, s68
	v_lshl_add_u64 v[62:63], s[36:37], 0, v[164:165]
	s_mov_b32 m0, s64
	s_nop 0
	global_load_lds_dwordx4 v[62:63], off
	v_lshl_add_u64 v[62:63], s[36:37], 0, v[162:163]
	s_add_i32 m0, s64, 0x2000
	s_nop 0
	global_load_lds_dwordx4 v[62:63], off
	s_waitcnt vmcnt(6)
	s_barrier
	v_mfma_f32_16x16x32_bf16 v[58:61], v[208:211], v[78:81], v[58:61]
	v_mfma_f32_16x16x32_bf16 v[50:53], v[226:229], v[78:81], v[50:53]
	v_mfma_f32_16x16x32_bf16 v[42:45], v[208:211], v[90:93], v[42:45]
	v_mfma_f32_16x16x32_bf16 v[34:37], v[226:229], v[90:93], v[34:37]
	v_mfma_f32_16x16x32_bf16 v[26:29], v[208:211], v[176:179], v[26:29]
	v_mfma_f32_16x16x32_bf16 v[18:21], v[226:229], v[176:179], v[18:21]
	v_mfma_f32_16x16x32_bf16 v[10:13], v[208:211], v[184:187], v[10:13]
	v_mfma_f32_16x16x32_bf16 v[2:5], v[226:229], v[184:187], v[2:5]
	v_mfma_f32_16x16x32_bf16 v[74:77], v[222:225], v[86:89], v[58:61]
	v_mfma_f32_16x16x32_bf16 v[50:53], v[230:233], v[86:89], v[50:53]
	v_mfma_f32_16x16x32_bf16 v[42:45], v[222:225], v[94:97], v[42:45]
	v_mfma_f32_16x16x32_bf16 v[34:37], v[230:233], v[94:97], v[34:37]
	v_mfma_f32_16x16x32_bf16 v[26:29], v[222:225], v[180:183], v[26:29]
	v_mfma_f32_16x16x32_bf16 v[18:21], v[230:233], v[180:183], v[18:21]
	v_mfma_f32_16x16x32_bf16 v[10:13], v[222:225], v[188:191], v[10:13]
	v_mfma_f32_16x16x32_bf16 v[2:5], v[230:233], v[188:191], v[2:5]
	s_add_i32 s83, s83, 2
	s_add_u32 s81, s81, 0x100
	s_addc_u32 s82, s82, 0
	s_cmp_gt_u32 s83, 13
	s_mov_b64 s[36:37], s[62:63]
	s_barrier
	s_cbranch_scc0 .LBB0_1099
	s_setprio 0
	v_lshl_or_b32 v58, s27, 8, v174
	v_mov_b32_e32 v177, v1
	v_ashrrev_i32_e32 v59, 31, v58
	v_lshlrev_b64 v[58:59], 2, v[58:59]
	v_lshl_add_u64 v[66:67], s[46:47], 0, v[58:59]
	v_lshl_add_u64 v[70:71], s[48:49], 0, v[58:59]
	v_lshlrev_b32_e32 v250, 2, v174
	v_add_u32_e32 v250, 0x20840, v250
	ds_read_b128 v[86:89], v250
	ds_read_b128 v[78:81], v250 offset:1024
	ds_read_b128 v[62:65], v250 offset:16
	ds_read_b128 v[58:61], v250 offset:1040
	ds_read_b128 v[94:97], v250 offset:512
	ds_read_b128 v[90:93], v250 offset:1536
	s_nop 0
	ds_read_b128 v[66:69], v250 offset:528
	s_nop 0
	ds_read_b128 v[70:73], v250 offset:1552
	s_lshl_b32 s3, s3, 8
	v_lshl_or_b32 v176, s27, 7, v174
	v_add_u32_e32 v184, s3, v177
	v_lshl_add_u32 v177, v177, 3, s33
	ds_read_b64 v[178:179], v177
	s_movk_i32 s27, 0xb00
	s_and_b64 vcc, exec, s[60:61]
	s_waitcnt lgkmcnt(0)
	ds_read_b64 v[230:231], v177 offset:128
	v_lshl_add_u32 v246, v171, 3, s33
	ds_read_b64 v[232:233], v246
	ds_read_b64 v[234:235], v246 offset:128
	v_lshl_add_u32 v247, v172, 3, s33
	ds_read_b64 v[236:237], v247
	ds_read_b64 v[238:239], v247 offset:128
	v_lshl_add_u32 v248, v173, 3, s33
	ds_read_b64 v[240:241], v248
	ds_read_b64 v[242:243], v248 offset:128
	v_xor_b32_e32 v89, 0x80000000, v89
	v_xor_b32_e32 v88, 0x80000000, v88
	v_pk_fma_f32 v[160:161], v[88:89], v[178:179], v[160:161] op_sel_hi:[1,0,1]
	v_pk_fma_f32 v[158:159], v[86:87], v[178:179], v[158:159] op_sel_hi:[1,0,1] neg_lo:[1,0,0] neg_hi:[1,0,0]
	v_pk_fma_f32 v[160:161], v[178:179], v[160:161], v[80:81] op_sel:[1,0,0]
	v_pk_fma_f32 v[158:159], v[178:179], v[158:159], v[78:79] op_sel:[1,0,0]
	v_pk_fma_f32 v[154:155], v[94:95], v[178:179], v[154:155] op_sel_hi:[1,0,1] neg_lo:[1,0,0] neg_hi:[1,0,0]
	v_mul_f32_e32 v182, 0xbfb8aa3b, v160
	v_pk_fma_f32 v[180:181], v[178:179], v[154:155], v[90:91] op_sel:[1,0,0]
	v_mul_f32_e32 v154, 0xbfb8aa3b, v158
	v_mul_f32_e32 v155, 0xbfb8aa3b, v159
	v_mul_f32_e32 v183, 0xbfb8aa3b, v161
	v_exp_f32_e32 v154, v154
	v_exp_f32_e32 v155, v155
	v_exp_f32_e32 v182, v182
	v_exp_f32_e32 v183, v183
	v_add_f32_e32 v154, 1.0, v154
	v_add_f32_e32 v155, 1.0, v155
	v_add_f32_e32 v182, 1.0, v182
	v_add_f32_e32 v183, 1.0, v183
	v_rcp_f32_e32 v154, v154
	v_rcp_f32_e32 v155, v155
	v_rcp_f32_e32 v182, v182
	v_rcp_f32_e32 v183, v183
	v_xor_b32_e32 v97, 0x80000000, v97
	v_xor_b32_e32 v96, 0x80000000, v96
	v_xor_b32_e32 v65, 0x80000000, v65
	v_xor_b32_e32 v64, 0x80000000, v64
	v_pk_fma_f32 v[156:157], v[96:97], v[178:179], v[156:157] op_sel_hi:[1,0,1]
	v_pk_fma_f32 v[152:153], v[64:65], v[178:179], v[152:153] op_sel_hi:[1,0,1]
	v_pk_fma_f32 v[150:151], v[62:63], v[178:179], v[150:151] op_sel_hi:[1,0,1] neg_lo:[1,0,0] neg_hi:[1,0,0]
	v_pk_fma_f32 v[156:157], v[178:179], v[156:157], v[92:93] op_sel:[1,0,0]
	v_pk_mul_f32 v[160:161], v[160:161], v[182:183]
	v_pk_mul_f32 v[158:159], v[158:159], v[154:155]
	v_pk_fma_f32 v[152:153], v[178:179], v[152:153], v[60:61] op_sel:[1,0,0]
	v_pk_fma_f32 v[150:151], v[178:179], v[150:151], v[58:59] op_sel:[1,0,0]
	v_pk_mul_f32 v[154:155], v[156:157], v[160:161]
	v_pk_mul_f32 v[156:157], v[180:181], v[158:159]
	v_mul_f32_e32 v158, 0xbfb8aa3b, v150
	v_mul_f32_e32 v159, 0xbfb8aa3b, v151
	v_mul_f32_e32 v160, 0xbfb8aa3b, v152
	v_mul_f32_e32 v161, 0xbfb8aa3b, v153
	v_exp_f32_e32 v158, v158
	v_exp_f32_e32 v159, v159
	v_exp_f32_e32 v160, v160
	v_exp_f32_e32 v161, v161
	v_add_f32_e32 v158, 1.0, v158
	v_add_f32_e32 v159, 1.0, v159
	v_add_f32_e32 v160, 1.0, v160
	v_add_f32_e32 v161, 1.0, v161
	v_rcp_f32_e32 v158, v158
	v_rcp_f32_e32 v159, v159
	v_rcp_f32_e32 v160, v160
	v_rcp_f32_e32 v161, v161
	v_xor_b32_e32 v69, 0x80000000, v69
	v_xor_b32_e32 v68, 0x80000000, v68
	v_pk_fma_f32 v[148:149], v[68:69], v[178:179], v[148:149] op_sel_hi:[1,0,1]
	v_pk_fma_f32 v[146:147], v[66:67], v[178:179], v[146:147] op_sel_hi:[1,0,1] neg_lo:[1,0,0] neg_hi:[1,0,0]
	v_pk_fma_f32 v[148:149], v[178:179], v[148:149], v[72:73] op_sel:[1,0,0]
	v_pk_fma_f32 v[146:147], v[178:179], v[146:147], v[70:71] op_sel:[1,0,0]
	v_pk_mul_f32 v[152:153], v[152:153], v[160:161]
	v_pk_mul_f32 v[150:151], v[150:151], v[158:159]
	v_mul_lo_u32 v158, v184, s27
	v_pk_mul_f32 v[152:153], v[148:149], v[152:153]
	v_pk_mul_f32 v[148:149], v[146:147], v[150:151]
	v_add_lshl_u32 v150, v158, v176, 1
	v_cvt_pk_bf16_f32 v146, v156, v157
	v_cvt_pk_bf16_f32 v147, v154, v155
	v_cvt_pk_bf16_f32 v148, v148, v149
	v_cvt_pk_bf16_f32 v149, v152, v153
	buffer_store_dwordx4 v[146:149], v150, s[28:31], 0 offen sc1
	s_nop 1
	v_mov_b64_e32 v[146:147], v[230:231]
	s_waitcnt lgkmcnt(0)
	v_pk_fma_f32 v[142:143], v[86:87], v[146:147], v[142:143] op_sel_hi:[1,0,1] neg_lo:[1,0,0] neg_hi:[1,0,0]
	s_nop 0
	v_pk_fma_f32 v[142:143], v[146:147], v[142:143], v[78:79] op_sel:[1,0,0]
	v_pk_fma_f32 v[144:145], v[88:89], v[146:147], v[144:145] op_sel_hi:[1,0,1]
	v_mul_f32_e32 v148, 0xbfb8aa3b, v142
	v_mul_f32_e32 v149, 0xbfb8aa3b, v143
	v_pk_fma_f32 v[144:145], v[146:147], v[144:145], v[80:81] op_sel:[1,0,0]
	v_exp_f32_e32 v148, v148
	v_exp_f32_e32 v149, v149
	v_mul_f32_e32 v150, 0xbfb8aa3b, v144
	v_mul_f32_e32 v151, 0xbfb8aa3b, v145
	v_exp_f32_e32 v150, v150
	v_exp_f32_e32 v151, v151
	v_add_f32_e32 v148, 1.0, v148
	v_add_f32_e32 v149, 1.0, v149
	v_rcp_f32_e32 v148, v148
	v_rcp_f32_e32 v149, v149
	v_add_f32_e32 v150, 1.0, v150
	v_add_f32_e32 v151, 1.0, v151
	v_rcp_f32_e32 v150, v150
	v_rcp_f32_e32 v151, v151
	v_pk_fma_f32 v[138:139], v[94:95], v[146:147], v[138:139] op_sel_hi:[1,0,1] neg_lo:[1,0,0] neg_hi:[1,0,0]
	v_pk_fma_f32 v[134:135], v[62:63], v[146:147], v[134:135] op_sel_hi:[1,0,1] neg_lo:[1,0,0] neg_hi:[1,0,0]
	v_pk_fma_f32 v[138:139], v[146:147], v[138:139], v[90:91] op_sel:[1,0,0]
	v_pk_mul_f32 v[142:143], v[142:143], v[148:149]
	v_pk_fma_f32 v[134:135], v[146:147], v[134:135], v[58:59] op_sel:[1,0,0]
	v_pk_fma_f32 v[140:141], v[96:97], v[146:147], v[140:141] op_sel_hi:[1,0,1]
	v_pk_mul_f32 v[138:139], v[138:139], v[142:143]
	v_pk_fma_f32 v[136:137], v[64:65], v[146:147], v[136:137] op_sel_hi:[1,0,1]
	v_mul_f32_e32 v142, 0xbfb8aa3b, v134
	v_mul_f32_e32 v143, 0xbfb8aa3b, v135
	v_pk_fma_f32 v[140:141], v[146:147], v[140:141], v[92:93] op_sel:[1,0,0]
	v_pk_mul_f32 v[144:145], v[144:145], v[150:151]
	v_pk_fma_f32 v[136:137], v[146:147], v[136:137], v[60:61] op_sel:[1,0,0]
	v_exp_f32_e32 v142, v142
	v_exp_f32_e32 v143, v143
	v_pk_mul_f32 v[140:141], v[140:141], v[144:145]
	v_mul_f32_e32 v144, 0xbfb8aa3b, v136
	v_mul_f32_e32 v145, 0xbfb8aa3b, v137
	v_exp_f32_e32 v144, v144
	v_exp_f32_e32 v145, v145
	v_add_f32_e32 v142, 1.0, v142
	v_add_f32_e32 v143, 1.0, v143
	v_rcp_f32_e32 v142, v142
	v_rcp_f32_e32 v143, v143
	v_add_f32_e32 v144, 1.0, v144
	v_add_f32_e32 v145, 1.0, v145
	v_rcp_f32_e32 v144, v144
	v_rcp_f32_e32 v145, v145
	v_pk_fma_f32 v[130:131], v[66:67], v[146:147], v[130:131] op_sel_hi:[1,0,1] neg_lo:[1,0,0] neg_hi:[1,0,0]
	v_pk_mul_f32 v[134:135], v[134:135], v[142:143]
	v_pk_fma_f32 v[130:131], v[146:147], v[130:131], v[70:71] op_sel:[1,0,0]
	v_pk_fma_f32 v[132:133], v[68:69], v[146:147], v[132:133] op_sel_hi:[1,0,1]
	v_pk_mul_f32 v[134:135], v[130:131], v[134:135]
	v_add_u32_e32 v130, 0xb000, v176
	v_pk_fma_f32 v[132:133], v[146:147], v[132:133], v[72:73] op_sel:[1,0,0]
	v_pk_mul_f32 v[136:137], v[136:137], v[144:145]
	v_add_lshl_u32 v131, v158, v130, 1
	v_pk_mul_f32 v[136:137], v[132:133], v[136:137]
	v_cvt_pk_bf16_f32 v132, v138, v139
	v_cvt_pk_bf16_f32 v133, v140, v141
	v_cvt_pk_bf16_f32 v134, v134, v135
	s_nop 0
	v_cvt_pk_bf16_f32 v135, v136, v137
	buffer_store_dwordx4 v[132:135], v131, s[28:31], 0 offen sc1
	v_mov_b32_e32 v131, v171
	s_nop 0
	v_add_u32_e32 v138, s3, v131
	v_lshl_add_u32 v131, v131, 3, s33
	s_nop 1
	v_mov_b64_e32 v[132:133], v[232:233]
	s_waitcnt lgkmcnt(0)
	v_pk_fma_f32 v[128:129], v[88:89], v[132:133], v[128:129] op_sel_hi:[1,0,1]
	v_pk_fma_f32 v[126:127], v[86:87], v[132:133], v[126:127] op_sel_hi:[1,0,1] neg_lo:[1,0,0] neg_hi:[1,0,0]
	v_pk_fma_f32 v[128:129], v[132:133], v[128:129], v[80:81] op_sel:[1,0,0]
	v_pk_fma_f32 v[126:127], v[132:133], v[126:127], v[78:79] op_sel:[1,0,0]
	v_mul_f32_e32 v136, 0xbfb8aa3b, v128
	v_mul_f32_e32 v134, 0xbfb8aa3b, v126
	v_mul_f32_e32 v135, 0xbfb8aa3b, v127
	v_mul_f32_e32 v137, 0xbfb8aa3b, v129
	v_exp_f32_e32 v134, v134
	v_exp_f32_e32 v135, v135
	v_exp_f32_e32 v136, v136
	v_exp_f32_e32 v137, v137
	v_add_f32_e32 v134, 1.0, v134
	v_add_f32_e32 v135, 1.0, v135
	v_add_f32_e32 v136, 1.0, v136
	v_add_f32_e32 v137, 1.0, v137
	v_rcp_f32_e32 v134, v134
	v_rcp_f32_e32 v135, v135
	v_rcp_f32_e32 v136, v136
	v_rcp_f32_e32 v137, v137
	v_pk_fma_f32 v[124:125], v[96:97], v[132:133], v[124:125] op_sel_hi:[1,0,1]
	v_pk_fma_f32 v[122:123], v[94:95], v[132:133], v[122:123] op_sel_hi:[1,0,1] neg_lo:[1,0,0] neg_hi:[1,0,0]
	v_pk_fma_f32 v[120:121], v[64:65], v[132:133], v[120:121] op_sel_hi:[1,0,1]
	v_pk_fma_f32 v[118:119], v[62:63], v[132:133], v[118:119] op_sel_hi:[1,0,1] neg_lo:[1,0,0] neg_hi:[1,0,0]
	v_pk_fma_f32 v[124:125], v[132:133], v[124:125], v[92:93] op_sel:[1,0,0]
	v_pk_fma_f32 v[122:123], v[132:133], v[122:123], v[90:91] op_sel:[1,0,0]
	v_pk_mul_f32 v[128:129], v[128:129], v[136:137]
	v_pk_mul_f32 v[126:127], v[126:127], v[134:135]
	v_pk_fma_f32 v[120:121], v[132:133], v[120:121], v[60:61] op_sel:[1,0,0]
	v_pk_fma_f32 v[118:119], v[132:133], v[118:119], v[58:59] op_sel:[1,0,0]
	v_pk_mul_f32 v[124:125], v[124:125], v[128:129]
	v_pk_mul_f32 v[122:123], v[122:123], v[126:127]
	v_mul_f32_e32 v126, 0xbfb8aa3b, v118
	v_mul_f32_e32 v127, 0xbfb8aa3b, v119
	v_mul_f32_e32 v128, 0xbfb8aa3b, v120
	v_mul_f32_e32 v129, 0xbfb8aa3b, v121
	v_exp_f32_e32 v126, v126
	v_exp_f32_e32 v127, v127
	v_exp_f32_e32 v128, v128
	v_exp_f32_e32 v129, v129
	v_add_f32_e32 v126, 1.0, v126
	v_add_f32_e32 v127, 1.0, v127
	v_add_f32_e32 v128, 1.0, v128
	v_add_f32_e32 v129, 1.0, v129
	v_rcp_f32_e32 v126, v126
	v_rcp_f32_e32 v127, v127
	v_rcp_f32_e32 v128, v128
	v_rcp_f32_e32 v129, v129
	v_pk_fma_f32 v[116:117], v[68:69], v[132:133], v[116:117] op_sel_hi:[1,0,1]
	v_pk_fma_f32 v[114:115], v[66:67], v[132:133], v[114:115] op_sel_hi:[1,0,1] neg_lo:[1,0,0] neg_hi:[1,0,0]
	v_pk_fma_f32 v[116:117], v[132:133], v[116:117], v[72:73] op_sel:[1,0,0]
	v_pk_fma_f32 v[114:115], v[132:133], v[114:115], v[70:71] op_sel:[1,0,0]
	v_pk_mul_f32 v[120:121], v[120:121], v[128:129]
	v_pk_mul_f32 v[118:119], v[118:119], v[126:127]
	v_mul_lo_u32 v126, v138, s27
	v_pk_mul_f32 v[120:121], v[116:117], v[120:121]
	v_pk_mul_f32 v[116:117], v[114:115], v[118:119]
	v_add_lshl_u32 v118, v126, v176, 1
	v_cvt_pk_bf16_f32 v114, v122, v123
	v_cvt_pk_bf16_f32 v115, v124, v125
	v_cvt_pk_bf16_f32 v116, v116, v117
	v_cvt_pk_bf16_f32 v117, v120, v121
	buffer_store_dwordx4 v[114:117], v118, s[28:31], 0 offen sc1
	s_nop 1
	v_mov_b64_e32 v[114:115], v[234:235]
	s_waitcnt lgkmcnt(0)
	v_pk_fma_f32 v[112:113], v[88:89], v[114:115], v[112:113] op_sel_hi:[1,0,1]
	v_pk_fma_f32 v[110:111], v[86:87], v[114:115], v[110:111] op_sel_hi:[1,0,1] neg_lo:[1,0,0] neg_hi:[1,0,0]
	v_pk_fma_f32 v[112:113], v[114:115], v[112:113], v[80:81] op_sel:[1,0,0]
	v_pk_fma_f32 v[110:111], v[114:115], v[110:111], v[78:79] op_sel:[1,0,0]
	v_mul_f32_e32 v118, 0xbfb8aa3b, v112
	v_mul_f32_e32 v116, 0xbfb8aa3b, v110
	v_mul_f32_e32 v117, 0xbfb8aa3b, v111
	v_mul_f32_e32 v119, 0xbfb8aa3b, v113
	v_exp_f32_e32 v116, v116
	v_exp_f32_e32 v117, v117
	v_exp_f32_e32 v118, v118
	v_exp_f32_e32 v119, v119
	v_add_f32_e32 v116, 1.0, v116
	v_add_f32_e32 v117, 1.0, v117
	v_add_f32_e32 v118, 1.0, v118
	v_add_f32_e32 v119, 1.0, v119
	v_rcp_f32_e32 v116, v116
	v_rcp_f32_e32 v117, v117
	v_rcp_f32_e32 v118, v118
	v_rcp_f32_e32 v119, v119
	v_pk_fma_f32 v[108:109], v[96:97], v[114:115], v[108:109] op_sel_hi:[1,0,1]
	v_pk_fma_f32 v[106:107], v[94:95], v[114:115], v[106:107] op_sel_hi:[1,0,1] neg_lo:[1,0,0] neg_hi:[1,0,0]
	v_pk_fma_f32 v[104:105], v[64:65], v[114:115], v[104:105] op_sel_hi:[1,0,1]
	v_pk_fma_f32 v[102:103], v[62:63], v[114:115], v[102:103] op_sel_hi:[1,0,1] neg_lo:[1,0,0] neg_hi:[1,0,0]
	v_pk_fma_f32 v[108:109], v[114:115], v[108:109], v[92:93] op_sel:[1,0,0]
	v_pk_fma_f32 v[106:107], v[114:115], v[106:107], v[90:91] op_sel:[1,0,0]
	v_pk_mul_f32 v[112:113], v[112:113], v[118:119]
	v_pk_mul_f32 v[110:111], v[110:111], v[116:117]
	v_pk_fma_f32 v[104:105], v[114:115], v[104:105], v[60:61] op_sel:[1,0,0]
	v_pk_fma_f32 v[102:103], v[114:115], v[102:103], v[58:59] op_sel:[1,0,0]
	v_pk_mul_f32 v[108:109], v[108:109], v[112:113]
	v_pk_mul_f32 v[106:107], v[106:107], v[110:111]
	v_mul_f32_e32 v110, 0xbfb8aa3b, v102
	v_mul_f32_e32 v111, 0xbfb8aa3b, v103
	v_mul_f32_e32 v112, 0xbfb8aa3b, v104
	v_mul_f32_e32 v113, 0xbfb8aa3b, v105
	v_exp_f32_e32 v110, v110
	v_exp_f32_e32 v111, v111
	v_exp_f32_e32 v112, v112
	v_exp_f32_e32 v113, v113
	v_add_f32_e32 v110, 1.0, v110
	v_add_f32_e32 v111, 1.0, v111
	v_add_f32_e32 v112, 1.0, v112
	v_add_f32_e32 v113, 1.0, v113
	v_rcp_f32_e32 v110, v110
	v_rcp_f32_e32 v111, v111
	v_rcp_f32_e32 v112, v112
	v_rcp_f32_e32 v113, v113
	v_pk_fma_f32 v[100:101], v[68:69], v[114:115], v[100:101] op_sel_hi:[1,0,1]
	v_pk_fma_f32 v[98:99], v[66:67], v[114:115], v[98:99] op_sel_hi:[1,0,1] neg_lo:[1,0,0] neg_hi:[1,0,0]
	v_pk_fma_f32 v[100:101], v[114:115], v[100:101], v[72:73] op_sel:[1,0,0]
	v_pk_fma_f32 v[98:99], v[114:115], v[98:99], v[70:71] op_sel:[1,0,0]
	v_pk_mul_f32 v[104:105], v[104:105], v[112:113]
	v_pk_mul_f32 v[102:103], v[102:103], v[110:111]
	v_pk_mul_f32 v[104:105], v[100:101], v[104:105]
	v_pk_mul_f32 v[100:101], v[98:99], v[102:103]
	v_add_lshl_u32 v102, v126, v130, 1
	v_cvt_pk_bf16_f32 v98, v106, v107
	v_cvt_pk_bf16_f32 v99, v108, v109
	v_cvt_pk_bf16_f32 v100, v100, v101
	v_cvt_pk_bf16_f32 v101, v104, v105
	buffer_store_dwordx4 v[98:101], v102, s[28:31], 0 offen sc1
	s_nop 1
	v_mov_b32_e32 v98, v172
	s_nop 0
	v_lshl_add_u32 v105, v98, 3, s33
	v_add_u32_e32 v104, s3, v98
	s_nop 1
	v_mov_b64_e32 v[98:99], v[236:237]
	s_waitcnt lgkmcnt(0)
	v_pk_fma_f32 v[84:85], v[88:89], v[98:99], v[84:85] op_sel_hi:[1,0,1]
	v_pk_fma_f32 v[82:83], v[86:87], v[98:99], v[82:83] op_sel_hi:[1,0,1] neg_lo:[1,0,0] neg_hi:[1,0,0]
	v_pk_fma_f32 v[84:85], v[98:99], v[84:85], v[80:81] op_sel:[1,0,0]
	v_pk_fma_f32 v[82:83], v[98:99], v[82:83], v[78:79] op_sel:[1,0,0]
	v_mul_f32_e32 v102, 0xbfb8aa3b, v84
	v_mul_f32_e32 v100, 0xbfb8aa3b, v82
	v_mul_f32_e32 v101, 0xbfb8aa3b, v83
	v_mul_f32_e32 v103, 0xbfb8aa3b, v85
	v_exp_f32_e32 v100, v100
	v_exp_f32_e32 v101, v101
	v_exp_f32_e32 v102, v102
	v_exp_f32_e32 v103, v103
	v_add_f32_e32 v100, 1.0, v100
	v_add_f32_e32 v101, 1.0, v101
	v_add_f32_e32 v102, 1.0, v102
	v_add_f32_e32 v103, 1.0, v103
	v_rcp_f32_e32 v100, v100
	v_rcp_f32_e32 v101, v101
	v_rcp_f32_e32 v102, v102
	v_rcp_f32_e32 v103, v103
	v_pk_fma_f32 v[76:77], v[96:97], v[98:99], v[76:77] op_sel_hi:[1,0,1]
	v_pk_fma_f32 v[74:75], v[94:95], v[98:99], v[74:75] op_sel_hi:[1,0,1] neg_lo:[1,0,0] neg_hi:[1,0,0]
	v_pk_fma_f32 v[56:57], v[64:65], v[98:99], v[56:57] op_sel_hi:[1,0,1]
	v_pk_fma_f32 v[54:55], v[62:63], v[98:99], v[54:55] op_sel_hi:[1,0,1] neg_lo:[1,0,0] neg_hi:[1,0,0]
	v_pk_fma_f32 v[76:77], v[98:99], v[76:77], v[92:93] op_sel:[1,0,0]
	v_pk_fma_f32 v[74:75], v[98:99], v[74:75], v[90:91] op_sel:[1,0,0]
	v_pk_mul_f32 v[84:85], v[84:85], v[102:103]
	v_pk_mul_f32 v[82:83], v[82:83], v[100:101]
	v_pk_fma_f32 v[56:57], v[98:99], v[56:57], v[60:61] op_sel:[1,0,0]
	v_pk_fma_f32 v[54:55], v[98:99], v[54:55], v[58:59] op_sel:[1,0,0]
	v_pk_mul_f32 v[76:77], v[76:77], v[84:85]
	v_pk_mul_f32 v[74:75], v[74:75], v[82:83]
	v_mul_f32_e32 v82, 0xbfb8aa3b, v54
	v_mul_f32_e32 v83, 0xbfb8aa3b, v55
	v_mul_f32_e32 v84, 0xbfb8aa3b, v56
	v_mul_f32_e32 v85, 0xbfb8aa3b, v57
	v_exp_f32_e32 v82, v82
	v_exp_f32_e32 v83, v83
	v_exp_f32_e32 v84, v84
	v_exp_f32_e32 v85, v85
	v_add_f32_e32 v82, 1.0, v82
	v_add_f32_e32 v83, 1.0, v83
	v_add_f32_e32 v84, 1.0, v84
	v_add_f32_e32 v85, 1.0, v85
	v_rcp_f32_e32 v82, v82
	v_rcp_f32_e32 v83, v83
	v_rcp_f32_e32 v84, v84
	v_rcp_f32_e32 v85, v85
	v_pk_fma_f32 v[52:53], v[68:69], v[98:99], v[52:53] op_sel_hi:[1,0,1]
	v_pk_fma_f32 v[50:51], v[66:67], v[98:99], v[50:51] op_sel_hi:[1,0,1] neg_lo:[1,0,0] neg_hi:[1,0,0]
	v_pk_fma_f32 v[52:53], v[98:99], v[52:53], v[72:73] op_sel:[1,0,0]
	v_pk_fma_f32 v[50:51], v[98:99], v[50:51], v[70:71] op_sel:[1,0,0]
	v_pk_mul_f32 v[56:57], v[56:57], v[84:85]
	v_pk_mul_f32 v[54:55], v[54:55], v[82:83]
	v_mul_lo_u32 v82, v104, s27
	v_pk_mul_f32 v[56:57], v[52:53], v[56:57]
	v_pk_mul_f32 v[52:53], v[50:51], v[54:55]
	v_add_lshl_u32 v54, v82, v176, 1
	v_cvt_pk_bf16_f32 v50, v74, v75
	v_cvt_pk_bf16_f32 v51, v76, v77
	v_cvt_pk_bf16_f32 v52, v52, v53
	v_cvt_pk_bf16_f32 v53, v56, v57
	buffer_store_dwordx4 v[50:53], v54, s[28:31], 0 offen sc1
	s_nop 1
	v_mov_b64_e32 v[50:51], v[238:239]
	s_waitcnt lgkmcnt(0)
	v_pk_fma_f32 v[48:49], v[88:89], v[50:51], v[48:49] op_sel_hi:[1,0,1]
	v_pk_fma_f32 v[46:47], v[86:87], v[50:51], v[46:47] op_sel_hi:[1,0,1] neg_lo:[1,0,0] neg_hi:[1,0,0]
	v_pk_fma_f32 v[48:49], v[50:51], v[48:49], v[80:81] op_sel:[1,0,0]
	v_pk_fma_f32 v[46:47], v[50:51], v[46:47], v[78:79] op_sel:[1,0,0]
	v_mul_f32_e32 v54, 0xbfb8aa3b, v48
	v_mul_f32_e32 v52, 0xbfb8aa3b, v46
	v_mul_f32_e32 v53, 0xbfb8aa3b, v47
	v_mul_f32_e32 v55, 0xbfb8aa3b, v49
	v_exp_f32_e32 v52, v52
	v_exp_f32_e32 v53, v53
	v_exp_f32_e32 v54, v54
	v_exp_f32_e32 v55, v55
	v_add_f32_e32 v52, 1.0, v52
	v_add_f32_e32 v53, 1.0, v53
	v_add_f32_e32 v54, 1.0, v54
	v_add_f32_e32 v55, 1.0, v55
	v_rcp_f32_e32 v52, v52
	v_rcp_f32_e32 v53, v53
	v_rcp_f32_e32 v54, v54
	v_rcp_f32_e32 v55, v55
	v_pk_fma_f32 v[44:45], v[96:97], v[50:51], v[44:45] op_sel_hi:[1,0,1]
	v_pk_fma_f32 v[42:43], v[94:95], v[50:51], v[42:43] op_sel_hi:[1,0,1] neg_lo:[1,0,0] neg_hi:[1,0,0]
	v_pk_fma_f32 v[40:41], v[64:65], v[50:51], v[40:41] op_sel_hi:[1,0,1]
	v_pk_fma_f32 v[38:39], v[62:63], v[50:51], v[38:39] op_sel_hi:[1,0,1] neg_lo:[1,0,0] neg_hi:[1,0,0]
	v_pk_fma_f32 v[44:45], v[50:51], v[44:45], v[92:93] op_sel:[1,0,0]
	v_pk_fma_f32 v[42:43], v[50:51], v[42:43], v[90:91] op_sel:[1,0,0]
	v_pk_mul_f32 v[48:49], v[48:49], v[54:55]
	v_pk_mul_f32 v[46:47], v[46:47], v[52:53]
	v_pk_fma_f32 v[40:41], v[50:51], v[40:41], v[60:61] op_sel:[1,0,0]
	v_pk_fma_f32 v[38:39], v[50:51], v[38:39], v[58:59] op_sel:[1,0,0]
	v_pk_mul_f32 v[44:45], v[44:45], v[48:49]
	v_pk_mul_f32 v[42:43], v[42:43], v[46:47]
	v_mul_f32_e32 v46, 0xbfb8aa3b, v38
	v_mul_f32_e32 v47, 0xbfb8aa3b, v39
	v_mul_f32_e32 v48, 0xbfb8aa3b, v40
	v_mul_f32_e32 v49, 0xbfb8aa3b, v41
	v_exp_f32_e32 v46, v46
	v_exp_f32_e32 v47, v47
	v_exp_f32_e32 v48, v48
	v_exp_f32_e32 v49, v49
	v_add_f32_e32 v46, 1.0, v46
	v_add_f32_e32 v47, 1.0, v47
	v_add_f32_e32 v48, 1.0, v48
	v_add_f32_e32 v49, 1.0, v49
	v_rcp_f32_e32 v46, v46
	v_rcp_f32_e32 v47, v47
	v_rcp_f32_e32 v48, v48
	v_rcp_f32_e32 v49, v49
	v_pk_fma_f32 v[36:37], v[68:69], v[50:51], v[36:37] op_sel_hi:[1,0,1]
	v_pk_fma_f32 v[34:35], v[66:67], v[50:51], v[34:35] op_sel_hi:[1,0,1] neg_lo:[1,0,0] neg_hi:[1,0,0]
	v_pk_fma_f32 v[36:37], v[50:51], v[36:37], v[72:73] op_sel:[1,0,0]
	v_pk_fma_f32 v[34:35], v[50:51], v[34:35], v[70:71] op_sel:[1,0,0]
	v_pk_mul_f32 v[40:41], v[40:41], v[48:49]
	v_pk_mul_f32 v[38:39], v[38:39], v[46:47]
	v_pk_mul_f32 v[40:41], v[36:37], v[40:41]
	v_pk_mul_f32 v[36:37], v[34:35], v[38:39]
	v_add_lshl_u32 v38, v82, v130, 1
	v_cvt_pk_bf16_f32 v34, v42, v43
	v_cvt_pk_bf16_f32 v35, v44, v45
	v_cvt_pk_bf16_f32 v36, v36, v37
	v_cvt_pk_bf16_f32 v37, v40, v41
	buffer_store_dwordx4 v[34:37], v38, s[28:31], 0 offen sc1
	s_nop 1
	v_mov_b32_e32 v34, v173
	s_nop 0
	v_lshl_add_u32 v41, v34, 3, s33
	v_add_u32_e32 v40, s3, v34
	s_nop 1
	v_mov_b64_e32 v[34:35], v[240:241]
	s_mov_b32 s3, s77
	s_waitcnt lgkmcnt(0)
	v_pk_fma_f32 v[32:33], v[88:89], v[34:35], v[32:33] op_sel_hi:[1,0,1]
	v_pk_fma_f32 v[30:31], v[86:87], v[34:35], v[30:31] op_sel_hi:[1,0,1] neg_lo:[1,0,0] neg_hi:[1,0,0]
	v_pk_fma_f32 v[32:33], v[34:35], v[32:33], v[80:81] op_sel:[1,0,0]
	v_pk_fma_f32 v[30:31], v[34:35], v[30:31], v[78:79] op_sel:[1,0,0]
	v_mul_f32_e32 v38, 0xbfb8aa3b, v32
	v_mul_f32_e32 v36, 0xbfb8aa3b, v30
	v_mul_f32_e32 v37, 0xbfb8aa3b, v31
	v_mul_f32_e32 v39, 0xbfb8aa3b, v33
	v_exp_f32_e32 v36, v36
	v_exp_f32_e32 v37, v37
	v_exp_f32_e32 v38, v38
	v_exp_f32_e32 v39, v39
	v_add_f32_e32 v36, 1.0, v36
	v_add_f32_e32 v37, 1.0, v37
	v_add_f32_e32 v38, 1.0, v38
	v_add_f32_e32 v39, 1.0, v39
	v_rcp_f32_e32 v36, v36
	v_rcp_f32_e32 v37, v37
	v_rcp_f32_e32 v38, v38
	v_rcp_f32_e32 v39, v39
	v_pk_fma_f32 v[28:29], v[96:97], v[34:35], v[28:29] op_sel_hi:[1,0,1]
	v_pk_fma_f32 v[26:27], v[94:95], v[34:35], v[26:27] op_sel_hi:[1,0,1] neg_lo:[1,0,0] neg_hi:[1,0,0]
	v_pk_fma_f32 v[24:25], v[64:65], v[34:35], v[24:25] op_sel_hi:[1,0,1]
	v_pk_fma_f32 v[22:23], v[62:63], v[34:35], v[22:23] op_sel_hi:[1,0,1] neg_lo:[1,0,0] neg_hi:[1,0,0]
	v_pk_fma_f32 v[28:29], v[34:35], v[28:29], v[92:93] op_sel:[1,0,0]
	v_pk_fma_f32 v[26:27], v[34:35], v[26:27], v[90:91] op_sel:[1,0,0]
	v_pk_mul_f32 v[32:33], v[32:33], v[38:39]
	v_pk_mul_f32 v[30:31], v[30:31], v[36:37]
	v_pk_fma_f32 v[24:25], v[34:35], v[24:25], v[60:61] op_sel:[1,0,0]
	v_pk_fma_f32 v[22:23], v[34:35], v[22:23], v[58:59] op_sel:[1,0,0]
	v_pk_mul_f32 v[28:29], v[28:29], v[32:33]
	v_pk_mul_f32 v[26:27], v[26:27], v[30:31]
	v_mul_f32_e32 v30, 0xbfb8aa3b, v22
	v_mul_f32_e32 v31, 0xbfb8aa3b, v23
	v_mul_f32_e32 v32, 0xbfb8aa3b, v24
	v_mul_f32_e32 v33, 0xbfb8aa3b, v25
	v_exp_f32_e32 v30, v30
	v_exp_f32_e32 v31, v31
	v_exp_f32_e32 v32, v32
	v_exp_f32_e32 v33, v33
	v_add_f32_e32 v30, 1.0, v30
	v_add_f32_e32 v31, 1.0, v31
	v_add_f32_e32 v32, 1.0, v32
	v_add_f32_e32 v33, 1.0, v33
	v_rcp_f32_e32 v30, v30
	v_rcp_f32_e32 v31, v31
	v_rcp_f32_e32 v32, v32
	v_rcp_f32_e32 v33, v33
	v_pk_fma_f32 v[20:21], v[68:69], v[34:35], v[20:21] op_sel_hi:[1,0,1]
	v_pk_fma_f32 v[18:19], v[66:67], v[34:35], v[18:19] op_sel_hi:[1,0,1] neg_lo:[1,0,0] neg_hi:[1,0,0]
	v_pk_fma_f32 v[20:21], v[34:35], v[20:21], v[72:73] op_sel:[1,0,0]
	v_pk_fma_f32 v[18:19], v[34:35], v[18:19], v[70:71] op_sel:[1,0,0]
	v_pk_mul_f32 v[24:25], v[24:25], v[32:33]
	v_pk_mul_f32 v[22:23], v[22:23], v[30:31]
	v_mul_lo_u32 v30, v40, s27
	v_pk_mul_f32 v[24:25], v[20:21], v[24:25]
	v_pk_mul_f32 v[20:21], v[18:19], v[22:23]
	v_add_lshl_u32 v22, v30, v176, 1
	v_cvt_pk_bf16_f32 v18, v26, v27
	v_cvt_pk_bf16_f32 v19, v28, v29
	v_cvt_pk_bf16_f32 v20, v20, v21
	v_cvt_pk_bf16_f32 v21, v24, v25
	buffer_store_dwordx4 v[18:21], v22, s[28:31], 0 offen sc1
	s_nop 1
	v_mov_b64_e32 v[18:19], v[242:243]
	s_mov_b32 s27, s58
	s_waitcnt lgkmcnt(0)
	v_pk_fma_f32 v[16:17], v[88:89], v[18:19], v[16:17] op_sel_hi:[1,0,1]
	v_pk_fma_f32 v[14:15], v[86:87], v[18:19], v[14:15] op_sel_hi:[1,0,1] neg_lo:[1,0,0] neg_hi:[1,0,0]
	v_pk_fma_f32 v[16:17], v[18:19], v[16:17], v[80:81] op_sel:[1,0,0]
	v_pk_fma_f32 v[14:15], v[18:19], v[14:15], v[78:79] op_sel:[1,0,0]
	v_mul_f32_e32 v22, 0xbfb8aa3b, v16
	v_mul_f32_e32 v20, 0xbfb8aa3b, v14
	v_mul_f32_e32 v21, 0xbfb8aa3b, v15
	v_mul_f32_e32 v23, 0xbfb8aa3b, v17
	v_exp_f32_e32 v20, v20
	v_exp_f32_e32 v21, v21
	v_exp_f32_e32 v22, v22
	v_exp_f32_e32 v23, v23
	v_add_f32_e32 v20, 1.0, v20
	v_add_f32_e32 v21, 1.0, v21
	v_add_f32_e32 v22, 1.0, v22
	v_add_f32_e32 v23, 1.0, v23
	v_rcp_f32_e32 v20, v20
	v_rcp_f32_e32 v21, v21
	v_rcp_f32_e32 v22, v22
	v_rcp_f32_e32 v23, v23
	v_pk_fma_f32 v[12:13], v[96:97], v[18:19], v[12:13] op_sel_hi:[1,0,1]
	v_pk_fma_f32 v[10:11], v[94:95], v[18:19], v[10:11] op_sel_hi:[1,0,1] neg_lo:[1,0,0] neg_hi:[1,0,0]
	v_pk_fma_f32 v[8:9], v[64:65], v[18:19], v[8:9] op_sel_hi:[1,0,1]
	v_pk_fma_f32 v[6:7], v[62:63], v[18:19], v[6:7] op_sel_hi:[1,0,1] neg_lo:[1,0,0] neg_hi:[1,0,0]
	v_pk_fma_f32 v[12:13], v[18:19], v[12:13], v[92:93] op_sel:[1,0,0]
	v_pk_fma_f32 v[10:11], v[18:19], v[10:11], v[90:91] op_sel:[1,0,0]
	v_pk_mul_f32 v[16:17], v[16:17], v[22:23]
	v_pk_mul_f32 v[14:15], v[14:15], v[20:21]
	v_pk_fma_f32 v[8:9], v[18:19], v[8:9], v[60:61] op_sel:[1,0,0]
	v_pk_fma_f32 v[6:7], v[18:19], v[6:7], v[58:59] op_sel:[1,0,0]
	v_pk_mul_f32 v[12:13], v[12:13], v[16:17]
	v_pk_mul_f32 v[10:11], v[10:11], v[14:15]
	v_mul_f32_e32 v14, 0xbfb8aa3b, v6
	v_mul_f32_e32 v15, 0xbfb8aa3b, v7
	v_mul_f32_e32 v16, 0xbfb8aa3b, v8
	v_mul_f32_e32 v17, 0xbfb8aa3b, v9
	v_exp_f32_e32 v14, v14
	v_exp_f32_e32 v15, v15
	v_exp_f32_e32 v16, v16
	v_exp_f32_e32 v17, v17
	v_add_f32_e32 v14, 1.0, v14
	v_add_f32_e32 v15, 1.0, v15
	v_add_f32_e32 v16, 1.0, v16
	v_add_f32_e32 v17, 1.0, v17
	v_rcp_f32_e32 v14, v14
	v_rcp_f32_e32 v15, v15
	v_rcp_f32_e32 v16, v16
	v_rcp_f32_e32 v17, v17
	v_pk_fma_f32 v[4:5], v[68:69], v[18:19], v[4:5] op_sel_hi:[1,0,1]
	v_pk_fma_f32 v[2:3], v[66:67], v[18:19], v[2:3] op_sel_hi:[1,0,1] neg_lo:[1,0,0] neg_hi:[1,0,0]
	v_pk_fma_f32 v[4:5], v[18:19], v[4:5], v[72:73] op_sel:[1,0,0]
	v_pk_fma_f32 v[2:3], v[18:19], v[2:3], v[70:71] op_sel:[1,0,0]
	v_pk_mul_f32 v[8:9], v[8:9], v[16:17]
	v_pk_mul_f32 v[6:7], v[6:7], v[14:15]
	v_pk_mul_f32 v[8:9], v[4:5], v[8:9]
	v_pk_mul_f32 v[4:5], v[2:3], v[6:7]
	v_add_lshl_u32 v6, v30, v130, 1
	v_cvt_pk_bf16_f32 v2, v10, v11
	v_cvt_pk_bf16_f32 v3, v12, v13
	v_cvt_pk_bf16_f32 v4, v4, v5
	v_cvt_pk_bf16_f32 v5, v8, v9
	buffer_store_dwordx4 v[2:5], v6, s[28:31], 0 offen sc1
	s_cbranch_vccz .LBB0_1098
	s_waitcnt vmcnt(0)
	v_readlane_b32 s76, v255, 13
	s_cmpk_gt_u32 s38, 0xff
	v_readlane_b32 s77, v255, 14
	s_cbranch_scc1 .LBB0_1103
	s_barrier
